# cache-policy hint: nt on the rowpass once-read h / Y loads and the h residual stores (XN stores and parameter vectors left default)
# baseline (speedup 1.0000x reference)
; __device__ __forceinline__ void phase_rowpass(const KArgs& A, int l, int wave, int lane, bool dummy = false) {
;     ...
;     for (int r = r0; r < r1; r += rs) {
;         const int b = r / TB, t = r % TB; const bool lat = t < SEQ; const int v = lat ? b : 8;
;         if (last && !lat) continue;
;         const size_t hoff = lat ? ((size_t)b * SEQ + t) * DM : ((size_t)b * CTXL + (t - SEQ)) * DM;
;         const float* hin = (l <= 1 ? (lat ? A.in[0] : A.in[2]) : (lat ? (const float*)A.out : (const float*)hctx)) + hoff;
;         float* hout = dummy ? (float*)(A.ws + OFF_K) + (size_t)r * DM : (lat ? A.out : hctx) + hoff;
;         f32x4 h[8];
; #pragma unroll
;         for (int j = 0; j < 8; ++j) h[j] = *(const f32x4*)(hin + 4 * lane + 256 * j);
;         if (!first) {
;             f32x4 y[8]; float ss = 0.f;
; #pragma unroll
;             for (int j = 0; j < 8; ++j) {
;                 if (lat || !GOUT_SPLIT) { const v2u w = *(const v2u*)(Y + (size_t)r * DM + 4 * lane + 256 * j); y[j] = (f32x4){bflo(w.x), bfhi(w.x), bflo(w.y), bfhi(w.y)}; }
.Lrp_loop:
	s_mul_hi_i32 s20, s12, 0x38e38e39
	s_lshr_b32 s21, s20, 31
	s_ashr_i32 s20, s20, 9
	s_add_i32 s20, s20, s21
	s_mul_i32 s21, s20, 0xfffff700
	s_add_i32 s21, s12, s21
	s_cmpk_lt_i32 s21, 0x800
	s_cselect_b64 s[38:39], -1, 0
	s_or_b64 s[38:39], s[10:11], s[38:39]
	s_and_b64 vcc, exec, s[38:39]
	s_cbranch_vccz .Lrp_next
	s_lshl_b32 s22, s20, 11
	s_add_i32 s22, s22, s21
	s_lshl_b32 s23, s20, 8
	s_add_i32 s23, s23, s21
	s_addk_i32 s23, 0xf800
	s_cmpk_lt_i32 s21, 0x800
	s_cselect_b32 s22, s22, s23
	s_cselect_b32 s24, s20, 8
	s_cselect_b32 s38, s14, s16
	s_cselect_b32 s39, s15, s17
	s_cselect_b64 s[20:21], -1, 0
	s_lshl_b32 s22, s22, 13
	s_add_u32 s38, s38, s22
	s_addc_u32 s39, s39, 0
	global_load_dwordx4 v[2:5], v178, s[38:39] nt
	global_load_dwordx4 v[6:9], v178, s[38:39] offset:1024 nt
	global_load_dwordx4 v[10:13], v178, s[38:39] offset:2048 nt
	global_load_dwordx4 v[14:17], v178, s[38:39] offset:3072 nt
	global_load_dwordx4 v[18:21], v180, s[38:39] nt
	global_load_dwordx4 v[22:25], v180, s[38:39] offset:1024 nt
	global_load_dwordx4 v[26:29], v180, s[38:39] offset:2048 nt
	global_load_dwordx4 v[30:33], v180, s[38:39] offset:3072 nt
	s_add_u32 s38, s94, 0x8900000
	s_addc_u32 s39, s95, 0
	s_cmp_lg_u64 s[20:21], 0
	s_cselect_b32 s38, s18, s38
	s_cselect_b32 s39, s19, s39
	s_add_u32 s22, s38, s22
	s_addc_u32 s23, s39, 0
	s_lshl_b32 s25, s12, 12
	s_and_b64 vcc, exec, s[6:7]
	s_cbranch_vccz .Lrp_noy
	s_add_u32 s38, s94, s25
	s_addc_u32 s39, s95, 0
	s_add_u32 s38, s38, 0xe400000
	s_addc_u32 s39, s39, 0
	global_load_dwordx2 v[34:35], v179, s[38:39] nt
	global_load_dwordx2 v[36:37], v179, s[38:39] offset:512 nt
	global_load_dwordx2 v[38:39], v179, s[38:39] offset:1024 nt
	global_load_dwordx2 v[40:41], v179, s[38:39] offset:1536 nt
	global_load_dwordx2 v[42:43], v179, s[38:39] offset:2048 nt
	global_load_dwordx2 v[44:45], v179, s[38:39] offset:2560 nt
	global_load_dwordx2 v[46:47], v179, s[38:39] offset:3072 nt
	global_load_dwordx2 v[48:49], v179, s[38:39] offset:3584 nt

; __device__ __forceinline__ void phase_rowpass(const KArgs& A, int l, int wave, int lane, bool dummy = false) {
;     ...
;                 if (lat || !GOUT_SPLIT) { const v2u w = *(const v2u*)(Y + (size_t)r * DM + 4 * lane + 256 * j); y[j] = (f32x4){bflo(w.x), bfhi(w.x), bflo(w.y), bfhi(w.y)}; }
;                 else { y[j] = (f32x4){0.f, 0.f, 0.f, 0.f};
; #pragma unroll
;                     for (int kq = 0; kq < 4; ++kq) { const v2u w = *(const v2u*)((const bf16_t*)(A.ws + OFF_V) + ((size_t)kq * 2048 + (size_t)b * CTXL + (t - SEQ)) * DM + 4 * lane + 256 * j);
;                         y[j] += (f32x4){bflo(w.x), bfhi(w.x), bflo(w.y), bfhi(w.y)}; } }
;                 ss += (y[j].x * y[j].x + y[j].y * y[j].y) + (y[j].z * y[j].z + y[j].w * y[j].w); }
;             const float rstd = 1.f / sqrtf(wave_sum(ss) * (1.f / DM) + NORM_EPS);
.Lrp_vec_ok:
	s_add_u32 s24, s94, s25
	s_addc_u32 s25, s95, 0
	s_add_u32 s24, s24, 0x9c00000
	s_addc_u32 s25, s25, 0
	s_waitcnt vmcnt(0)
	s_and_b64 vcc, exec, s[6:7]
	s_cbranch_vccz .Lrp_second
	v_lshlrev_b32_e32 v228, 16, v34
	v_and_b32_e32 v229, s3, v34
	v_mul_f32_e32 v224, v228, v228
	v_mul_f32_e32 v225, v229, v229
	v_lshlrev_b32_e32 v228, 16, v35
	v_and_b32_e32 v229, s3, v35
	v_mul_f32_e32 v226, v228, v228
	v_mul_f32_e32 v227, v229, v229
	v_lshlrev_b32_e32 v228, 16, v36
	v_and_b32_e32 v229, s3, v36
	v_fmac_f32_e32 v224, v228, v228
	v_fmac_f32_e32 v225, v229, v229
	v_lshlrev_b32_e32 v228, 16, v37
	v_and_b32_e32 v229, s3, v37
	v_fmac_f32_e32 v226, v228, v228
	v_fmac_f32_e32 v227, v229, v229
	v_lshlrev_b32_e32 v228, 16, v38
	v_and_b32_e32 v229, s3, v38
	v_fmac_f32_e32 v224, v228, v228
	v_fmac_f32_e32 v225, v229, v229
	v_lshlrev_b32_e32 v228, 16, v39
	v_and_b32_e32 v229, s3, v39
	v_fmac_f32_e32 v226, v228, v228
	v_fmac_f32_e32 v227, v229, v229
	v_lshlrev_b32_e32 v228, 16, v40
	v_and_b32_e32 v229, s3, v40
	v_fmac_f32_e32 v224, v228, v228
	v_fmac_f32_e32 v225, v229, v229
	v_lshlrev_b32_e32 v228, 16, v41
	v_and_b32_e32 v229, s3, v41
	v_fmac_f32_e32 v226, v228, v228
	v_fmac_f32_e32 v227, v229, v229
	v_lshlrev_b32_e32 v228, 16, v42
	v_and_b32_e32 v229, s3, v42
	v_fmac_f32_e32 v224, v228, v228
	v_fmac_f32_e32 v225, v229, v229
	v_lshlrev_b32_e32 v228, 16, v43
	v_and_b32_e32 v229, s3, v43
	v_fmac_f32_e32 v226, v228, v228
	v_fmac_f32_e32 v227, v229, v229
	v_lshlrev_b32_e32 v228, 16, v44
	v_and_b32_e32 v229, s3, v44
	v_fmac_f32_e32 v224, v228, v228
	v_fmac_f32_e32 v225, v229, v229
	v_lshlrev_b32_e32 v228, 16, v45
	v_and_b32_e32 v229, s3, v45
	v_fmac_f32_e32 v226, v228, v228
	v_fmac_f32_e32 v227, v229, v229
	v_lshlrev_b32_e32 v228, 16, v46
	v_and_b32_e32 v229, s3, v46
	v_fmac_f32_e32 v224, v228, v228
	v_fmac_f32_e32 v225, v229, v229
	v_lshlrev_b32_e32 v228, 16, v47
	v_and_b32_e32 v229, s3, v47
	v_fmac_f32_e32 v226, v228, v228
	v_fmac_f32_e32 v227, v229, v229
	v_lshlrev_b32_e32 v228, 16, v48
	v_and_b32_e32 v229, s3, v48
	v_fmac_f32_e32 v224, v228, v228
	v_fmac_f32_e32 v225, v229, v229
	v_lshlrev_b32_e32 v228, 16, v49
	v_and_b32_e32 v229, s3, v49
	v_fmac_f32_e32 v226, v228, v228
	v_fmac_f32_e32 v227, v229, v229
	v_add_f32_e32 v224, v224, v225
	v_add_f32_e32 v226, v226, v227
	v_add_f32_e32 v224, v224, v226
	s_nop 1
	v_add_f32_dpp v224, v224, v224 quad_perm:[1,0,3,2] row_mask:0xf bank_mask:0xf
	s_nop 1
	v_add_f32_dpp v224, v224, v224 quad_perm:[2,3,0,1] row_mask:0xf bank_mask:0xf
	s_nop 1
	v_add_f32_dpp v224, v224, v224 row_half_mirror row_mask:0xf bank_mask:0xf
	s_nop 1
	v_add_f32_dpp v224, v224, v224 row_mirror row_mask:0xf bank_mask:0xf
	s_nop 1
	v_readlane_b32 s20, v224, 0
	v_readlane_b32 s21, v224, 16
	v_readlane_b32 s38, v224, 32
	v_readlane_b32 s39, v224, 48
	s_nop 2
	v_mov_b32_e32 v224, s20
	v_add_f32_e32 v224, s21, v224
	v_add_f32_e32 v224, s38, v224
	v_add_f32_e32 v224, s39, v224
	v_fmamk_f32 v240, v224, 0x3a000000, v186
	v_mul_f32_e32 v241, 0x4f800000, v240
	v_cmp_gt_f32_e32 vcc, s54, v240
	s_nop 1
	v_cndmask_b32_e32 v240, v240, v241, vcc
	v_sqrt_f32_e32 v241, v240
	s_nop 0
	v_add_u32_e32 v242, -1, v241
	v_fma_f32 v243, -v242, v241, v240
	v_cmp_ge_f32_e64 s[38:39], 0, v243
	v_add_u32_e32 v243, 1, v241
	s_nop 0
	v_cndmask_b32_e64 v242, v241, v242, s[38:39]
	v_fma_f32 v241, -v243, v241, v240
	v_cmp_lt_f32_e64 s[38:39], 0, v241
	s_nop 1
	v_cndmask_b32_e64 v241, v242, v243, s[38:39]
	v_mul_f32_e32 v242, 0x37800000, v241
	v_cndmask_b32_e32 v241, v241, v242, vcc
	v_cmp_class_f32_e32 vcc, v240, v187
	s_nop 1
	v_cndmask_b32_e32 v240, v241, v240, vcc
	v_div_scale_f32 v241, s[20:21], v240, v240, 1.0
	v_rcp_f32_e32 v242, v241
	s_nop 0
	v_fma_f32 v243, -v241, v242, 1.0
	v_fmac_f32_e32 v242, v243, v242
	v_div_scale_f32 v243, vcc, 1.0, v240, 1.0
	v_mul_f32_e32 v244, v243, v242
	v_fma_f32 v245, -v241, v244, v243
	v_fmac_f32_e32 v244, v245, v242
	v_fma_f32 v241, -v241, v244, v243
	v_div_fmas_f32 v241, v241, v242, v244
	v_div_fixup_f32 v230, v241, v240, 1.0
	v_lshlrev_b32_e32 v224, 16, v34
	v_and_b32_e32 v225, s3, v34
; __device__ __forceinline__ void phase_rowpass(const KArgs& A, int l, int wave, int lane, bool dummy = false) {
;     ...
; #pragma unroll
;             for (int j = 0; j < 8; ++j) { const int c = 4 * lane + 256 * j; const f32x4 gt = *(const f32x4*)(gate + c), pg = *(const f32x4*)(post_g + c);
;                 h[j] += gt * (y[j] * rstd * pg); *(f32x4*)(hout + c) = h[j]; }
	v_lshlrev_b32_e32 v226, 16, v35
	v_and_b32_e32 v227, s3, v35
	v_pk_mul_f32 v[224:225], v[230:231], v[224:225] op_sel_hi:[0,1]
	v_pk_mul_f32 v[226:227], v[230:231], v[226:227] op_sel_hi:[0,1]
	v_pk_mul_f32 v[224:225], v[82:83], v[224:225]
	v_pk_mul_f32 v[226:227], v[84:85], v[226:227]
	v_pk_fma_f32 v[2:3], v[50:51], v[224:225], v[2:3]
	v_pk_fma_f32 v[4:5], v[52:53], v[226:227], v[4:5]
	global_store_dwordx4 v178, v[2:5], s[22:23] nt
	v_lshlrev_b32_e32 v224, 16, v36
	v_and_b32_e32 v225, s3, v36
	v_lshlrev_b32_e32 v226, 16, v37
	v_and_b32_e32 v227, s3, v37
	v_pk_mul_f32 v[224:225], v[230:231], v[224:225] op_sel_hi:[0,1]
	v_pk_mul_f32 v[226:227], v[230:231], v[226:227] op_sel_hi:[0,1]
	v_pk_mul_f32 v[224:225], v[86:87], v[224:225]
	v_pk_mul_f32 v[226:227], v[88:89], v[226:227]
	v_pk_fma_f32 v[6:7], v[54:55], v[224:225], v[6:7]
	v_pk_fma_f32 v[8:9], v[56:57], v[226:227], v[8:9]
	global_store_dwordx4 v178, v[6:9], s[22:23] offset:1024 nt
	v_lshlrev_b32_e32 v224, 16, v38
	v_and_b32_e32 v225, s3, v38
	v_lshlrev_b32_e32 v226, 16, v39
	v_and_b32_e32 v227, s3, v39
	v_pk_mul_f32 v[224:225], v[230:231], v[224:225] op_sel_hi:[0,1]
	v_pk_mul_f32 v[226:227], v[230:231], v[226:227] op_sel_hi:[0,1]
	v_pk_mul_f32 v[224:225], v[90:91], v[224:225]
	v_pk_mul_f32 v[226:227], v[92:93], v[226:227]
	v_pk_fma_f32 v[10:11], v[58:59], v[224:225], v[10:11]
	v_pk_fma_f32 v[12:13], v[60:61], v[226:227], v[12:13]
	global_store_dwordx4 v178, v[10:13], s[22:23] offset:2048 nt
	v_lshlrev_b32_e32 v224, 16, v40
	v_and_b32_e32 v225, s3, v40
	v_lshlrev_b32_e32 v226, 16, v41
	v_and_b32_e32 v227, s3, v41
	v_pk_mul_f32 v[224:225], v[230:231], v[224:225] op_sel_hi:[0,1]
	v_pk_mul_f32 v[226:227], v[230:231], v[226:227] op_sel_hi:[0,1]
	v_pk_mul_f32 v[224:225], v[94:95], v[224:225]
	v_pk_mul_f32 v[226:227], v[96:97], v[226:227]
	v_pk_fma_f32 v[14:15], v[62:63], v[224:225], v[14:15]
	v_pk_fma_f32 v[16:17], v[64:65], v[226:227], v[16:17]
	global_store_dwordx4 v178, v[14:17], s[22:23] offset:3072 nt
	v_lshlrev_b32_e32 v224, 16, v42
	v_and_b32_e32 v225, s3, v42
	v_lshlrev_b32_e32 v226, 16, v43
	v_and_b32_e32 v227, s3, v43
	v_pk_mul_f32 v[224:225], v[230:231], v[224:225] op_sel_hi:[0,1]
	v_pk_mul_f32 v[226:227], v[230:231], v[226:227] op_sel_hi:[0,1]
	v_pk_mul_f32 v[224:225], v[98:99], v[224:225]
	v_pk_mul_f32 v[226:227], v[100:101], v[226:227]
	v_pk_fma_f32 v[18:19], v[66:67], v[224:225], v[18:19]
	v_pk_fma_f32 v[20:21], v[68:69], v[226:227], v[20:21]
	global_store_dwordx4 v180, v[18:21], s[22:23] nt
	v_lshlrev_b32_e32 v224, 16, v44
	v_and_b32_e32 v225, s3, v44
	v_lshlrev_b32_e32 v226, 16, v45
	v_and_b32_e32 v227, s3, v45
	v_pk_mul_f32 v[224:225], v[230:231], v[224:225] op_sel_hi:[0,1]
	v_pk_mul_f32 v[226:227], v[230:231], v[226:227] op_sel_hi:[0,1]
	v_pk_mul_f32 v[224:225], v[102:103], v[224:225]
	v_pk_mul_f32 v[226:227], v[104:105], v[226:227]
	v_pk_fma_f32 v[22:23], v[70:71], v[224:225], v[22:23]
	v_pk_fma_f32 v[24:25], v[72:73], v[226:227], v[24:25]
	global_store_dwordx4 v180, v[22:25], s[22:23] offset:1024 nt
	v_lshlrev_b32_e32 v224, 16, v46
	v_and_b32_e32 v225, s3, v46
	v_lshlrev_b32_e32 v226, 16, v47
	v_and_b32_e32 v227, s3, v47
	v_pk_mul_f32 v[224:225], v[230:231], v[224:225] op_sel_hi:[0,1]
	v_pk_mul_f32 v[226:227], v[230:231], v[226:227] op_sel_hi:[0,1]
	v_pk_mul_f32 v[224:225], v[106:107], v[224:225]
	v_pk_mul_f32 v[226:227], v[108:109], v[226:227]
	v_pk_fma_f32 v[26:27], v[74:75], v[224:225], v[26:27]
	v_pk_fma_f32 v[28:29], v[76:77], v[226:227], v[28:29]
	global_store_dwordx4 v180, v[26:29], s[22:23] offset:2048 nt
	v_lshlrev_b32_e32 v224, 16, v48
	v_and_b32_e32 v225, s3, v48
	v_lshlrev_b32_e32 v226, 16, v49
	v_and_b32_e32 v227, s3, v49
	v_pk_mul_f32 v[224:225], v[230:231], v[224:225] op_sel_hi:[0,1]
	v_pk_mul_f32 v[226:227], v[230:231], v[226:227] op_sel_hi:[0,1]
	v_pk_mul_f32 v[224:225], v[110:111], v[224:225]
	v_pk_mul_f32 v[226:227], v[112:113], v[226:227]
	v_pk_fma_f32 v[30:31], v[78:79], v[224:225], v[30:31]
	v_pk_fma_f32 v[32:33], v[80:81], v[226:227], v[32:33]
	global_store_dwordx4 v180, v[30:33], s[22:23] offset:3072 nt
